# peeled srcC=0 first iteration extended to UQ/UKV/split-K GEMM instances; their pre-guard zeroing moved onto the zero-trip path
# baseline (speedup 1.0000x reference)
.LBB0_614:
	s_andn2_b64 vcc, exec, s[12:13]
	s_cbranch_vccz .Lnz_uq
	v_mov_b32_e32 v131, 0
	v_mov_b32_e32 v130, v131
	v_mov_b32_e32 v129, v131
	v_mov_b32_e32 v128, v131
	v_mov_b32_e32 v127, v131
	v_mov_b32_e32 v126, v131
	v_mov_b32_e32 v125, v131
	v_mov_b32_e32 v124, v131
	v_mov_b32_e32 v115, v131
	v_mov_b32_e32 v114, v131
	v_mov_b32_e32 v113, v131
	v_mov_b32_e32 v112, v131
	v_mov_b32_e32 v111, v131
	v_mov_b32_e32 v110, v131
	v_mov_b32_e32 v109, v131
	v_mov_b32_e32 v108, v131
	v_mov_b32_e32 v95, v131
	v_mov_b32_e32 v94, v131
	v_mov_b32_e32 v93, v131
	v_mov_b32_e32 v92, v131
	v_mov_b32_e32 v91, v131
	v_mov_b32_e32 v90, v131
	v_mov_b32_e32 v89, v131
	v_mov_b32_e32 v88, v131
	v_mov_b32_e32 v79, v131
	v_mov_b32_e32 v78, v131
	v_mov_b32_e32 v77, v131
	v_mov_b32_e32 v76, v131
	v_mov_b32_e32 v75, v131
	v_mov_b32_e32 v74, v131
	v_mov_b32_e32 v73, v131
	v_mov_b32_e32 v72, v131
	v_mov_b32_e32 v123, v131
	v_mov_b32_e32 v122, v131
	v_mov_b32_e32 v121, v131
	v_mov_b32_e32 v120, v131
	v_mov_b32_e32 v119, v131
	v_mov_b32_e32 v118, v131
	v_mov_b32_e32 v117, v131
	v_mov_b32_e32 v116, v131
	v_mov_b32_e32 v107, v131
	v_mov_b32_e32 v106, v131
	v_mov_b32_e32 v105, v131
	v_mov_b32_e32 v104, v131
	v_mov_b32_e32 v103, v131
	v_mov_b32_e32 v102, v131
	v_mov_b32_e32 v101, v131
	v_mov_b32_e32 v100, v131
	v_mov_b32_e32 v87, v131
	v_mov_b32_e32 v86, v131
	v_mov_b32_e32 v85, v131
	v_mov_b32_e32 v84, v131
	v_mov_b32_e32 v83, v131
	v_mov_b32_e32 v82, v131
	v_mov_b32_e32 v81, v131
	v_mov_b32_e32 v80, v131
	v_mov_b32_e32 v71, v131
	v_mov_b32_e32 v70, v131
	v_mov_b32_e32 v69, v131
	v_mov_b32_e32 v68, v131
	v_mov_b32_e32 v67, v131
	v_mov_b32_e32 v66, v131
	v_mov_b32_e32 v65, v131
	v_mov_b32_e32 v64, v131
	v_mov_b32_e32 v63, v131
	v_mov_b32_e32 v62, v131
	v_mov_b32_e32 v61, v131
	v_mov_b32_e32 v60, v131
	v_mov_b32_e32 v59, v131
	v_mov_b32_e32 v58, v131
	v_mov_b32_e32 v57, v131
	v_mov_b32_e32 v56, v131
	v_mov_b32_e32 v47, v131
	v_mov_b32_e32 v46, v131
	v_mov_b32_e32 v45, v131
	v_mov_b32_e32 v44, v131
	v_mov_b32_e32 v43, v131
	v_mov_b32_e32 v42, v131
	v_mov_b32_e32 v41, v131
	v_mov_b32_e32 v40, v131
	v_mov_b32_e32 v31, v131
	v_mov_b32_e32 v30, v131
	v_mov_b32_e32 v29, v131
	v_mov_b32_e32 v28, v131
	v_mov_b32_e32 v27, v131
	v_mov_b32_e32 v26, v131
	v_mov_b32_e32 v25, v131
	v_mov_b32_e32 v24, v131
	v_mov_b32_e32 v15, v131
	v_mov_b32_e32 v14, v131
	v_mov_b32_e32 v13, v131
	v_mov_b32_e32 v12, v131
	v_mov_b32_e32 v11, v131
	v_mov_b32_e32 v10, v131
	v_mov_b32_e32 v9, v131
	v_mov_b32_e32 v8, v131
	v_mov_b32_e32 v55, v131
	v_mov_b32_e32 v54, v131
	v_mov_b32_e32 v53, v131
	v_mov_b32_e32 v52, v131
	v_mov_b32_e32 v51, v131
	v_mov_b32_e32 v50, v131
	v_mov_b32_e32 v49, v131
	v_mov_b32_e32 v48, v131
	v_mov_b32_e32 v39, v131
	v_mov_b32_e32 v38, v131
	v_mov_b32_e32 v37, v131
	v_mov_b32_e32 v36, v131
	v_mov_b32_e32 v35, v131
	v_mov_b32_e32 v34, v131
	v_mov_b32_e32 v33, v131
	v_mov_b32_e32 v32, v131
	v_mov_b32_e32 v23, v131
	v_mov_b32_e32 v22, v131
	v_mov_b32_e32 v21, v131
	v_mov_b32_e32 v20, v131
	v_mov_b32_e32 v19, v131
	v_mov_b32_e32 v18, v131
	v_mov_b32_e32 v17, v131
	v_mov_b32_e32 v16, v131
	v_mov_b32_e32 v7, v131
	v_mov_b32_e32 v6, v131
	v_mov_b32_e32 v5, v131
	v_mov_b32_e32 v4, v131
	v_mov_b32_e32 v3, v131
	v_mov_b32_e32 v2, v131
	v_mov_b32_e32 v1, v131
	v_mov_b32_e32 v0, v131
	s_branch .LBB0_617
.Lnz_uq:
	s_add_u32 s25, s44, 0x100
	s_addc_u32 s26, s45, 0
	s_add_u32 s42, s46, 0x80
	s_addc_u32 s43, s47, 0
	s_mov_b32 s27, 0
	s_add_i32 s46, s27, 2
	s_add_u32 s20, s42, 0x80
	s_addc_u32 s21, s43, 0
	s_add_i32 s23, 0, 0x10000
	s_cmp_eq_u32 s67, s27
	s_cselect_b32 s45, s17, s21
	s_cselect_b32 s44, s16, s20
	v_add_u32_e32 v98, s23, v156
	s_cselect_b32 s49, s19, s26
	s_cselect_b32 s48, s18, s25
	s_add_i32 s20, 0, 0x14000
	ds_read_b128 v[142:145], v98
	ds_read_b128 v[158:161], v98 offset:1024
	ds_read_b128 v[162:165], v98 offset:2048
	ds_read_b128 v[166:169], v98 offset:3072
	v_add_u32_e32 v98, s20, v156
	ds_read_b128 v[170:173], v98
	ds_read_b128 v[174:177], v98 offset:1024
	ds_read_b128 v[188:191], v98 offset:2048
	ds_read_b128 v[192:195], v98 offset:3072
	v_lshl_add_u64 v[178:179], s[42:43], 0, v[140:141]
	s_add_i32 m0, s57, 0xc000
	ds_read_b128 v[196:199], v157
	ds_read_b128 v[200:203], v157 offset:1024
	ds_read_b128 v[204:207], v157 offset:2048
	ds_read_b128 v[208:211], v157 offset:3072
	ds_read_b128 v[212:215], v157 offset:4096
	ds_read_b128 v[216:219], v157 offset:5120
	ds_read_b128 v[238:241], v157 offset:6144
	ds_read_b128 v[242:245], v157 offset:7168
	global_load_lds_dwordx4 v[178:179], off
	v_lshl_add_u64 v[178:179], s[42:43], 0, v[138:139]
	s_add_i32 m0, s57, 0xe000
	s_nop 0
	global_load_lds_dwordx4 v[178:179], off
	s_waitcnt vmcnt(8)
	s_waitcnt lgkmcnt(0)
	s_barrier
	s_setprio 1
	s_waitcnt lgkmcnt(0)
	v_mfma_f32_16x16x32_bf16 v[128:131], v[142:145], v[196:199], 0
	v_mfma_f32_16x16x32_bf16 v[124:127], v[162:165], v[196:199], 0
	v_mfma_f32_16x16x32_bf16 v[112:115], v[142:145], v[204:207], 0
	v_mfma_f32_16x16x32_bf16 v[108:111], v[162:165], v[204:207], 0
	v_mfma_f32_16x16x32_bf16 v[92:95], v[142:145], v[212:215], 0
	v_mfma_f32_16x16x32_bf16 v[88:91], v[162:165], v[212:215], 0
	v_mfma_f32_16x16x32_bf16 v[76:79], v[142:145], v[238:241], 0
	v_mfma_f32_16x16x32_bf16 v[72:75], v[162:165], v[238:241], 0
	v_mfma_f32_16x16x32_bf16 v[128:131], v[158:161], v[200:203], v[128:131]
	v_mfma_f32_16x16x32_bf16 v[124:127], v[166:169], v[200:203], v[124:127]
	v_mfma_f32_16x16x32_bf16 v[112:115], v[158:161], v[208:211], v[112:115]
	v_mfma_f32_16x16x32_bf16 v[108:111], v[166:169], v[208:211], v[108:111]
	v_mfma_f32_16x16x32_bf16 v[92:95], v[158:161], v[216:219], v[92:95]
	v_mfma_f32_16x16x32_bf16 v[88:91], v[166:169], v[216:219], v[88:91]
	v_mfma_f32_16x16x32_bf16 v[76:79], v[158:161], v[242:245], v[76:79]
	v_mfma_f32_16x16x32_bf16 v[72:75], v[166:169], v[242:245], v[72:75]
	s_setprio 0
	s_setprio 1
	v_mfma_f32_16x16x32_bf16 v[120:123], v[170:173], v[196:199], 0
	v_mfma_f32_16x16x32_bf16 v[116:119], v[188:191], v[196:199], 0
	v_mfma_f32_16x16x32_bf16 v[104:107], v[170:173], v[204:207], 0
	v_mfma_f32_16x16x32_bf16 v[100:103], v[188:191], v[204:207], 0
	v_mfma_f32_16x16x32_bf16 v[84:87], v[170:173], v[212:215], 0
	v_mfma_f32_16x16x32_bf16 v[80:83], v[188:191], v[212:215], 0
	v_mfma_f32_16x16x32_bf16 v[68:71], v[170:173], v[238:241], 0
	v_mfma_f32_16x16x32_bf16 v[64:67], v[188:191], v[238:241], 0
	v_mfma_f32_16x16x32_bf16 v[120:123], v[174:177], v[200:203], v[120:123]
	v_mfma_f32_16x16x32_bf16 v[116:119], v[192:195], v[200:203], v[116:119]
	v_mfma_f32_16x16x32_bf16 v[104:107], v[174:177], v[208:211], v[104:107]
	v_mfma_f32_16x16x32_bf16 v[100:103], v[192:195], v[208:211], v[100:103]
	v_mfma_f32_16x16x32_bf16 v[84:87], v[174:177], v[216:219], v[84:87]
	v_mfma_f32_16x16x32_bf16 v[80:83], v[192:195], v[216:219], v[80:83]
	v_mfma_f32_16x16x32_bf16 v[68:71], v[174:177], v[242:245], v[68:71]
	v_mfma_f32_16x16x32_bf16 v[64:67], v[192:195], v[242:245], v[64:67]
	s_setprio 0
	s_barrier
	s_add_i32 s21, s23, s56
	v_lshl_add_u64 v[178:179], s[48:49], 0, v[132:133]
	s_mov_b32 m0, s21
	ds_read_b128 v[196:199], v157 offset:16384
	ds_read_b128 v[200:203], v157 offset:17408
	ds_read_b128 v[204:207], v157 offset:18432
	ds_read_b128 v[208:211], v157 offset:19456
	ds_read_b128 v[212:215], v157 offset:20480
	ds_read_b128 v[216:219], v157 offset:21504
	ds_read_b128 v[238:241], v157 offset:22528
	ds_read_b128 v[242:245], v157 offset:23552
	global_load_lds_dwordx4 v[178:179], off
	s_add_i32 m0, s21, 0x2000
	v_lshl_add_u64 v[220:221], s[48:49], 0, v[96:97]
	s_add_u32 s48, s48, s6
	s_addc_u32 s49, s49, s7
	s_add_i32 s20, s20, s56
	global_load_lds_dwordx4 v[220:221], off
	v_lshl_add_u64 v[234:235], s[48:49], 0, v[132:133]
	s_mov_b32 m0, s20
	v_lshl_add_u64 v[236:237], s[48:49], 0, v[96:97]
	global_load_lds_dwordx4 v[234:235], off
	s_add_i32 m0, s20, 0x2000
	v_lshl_add_u64 v[246:247], s[44:45], 0, v[132:133]
	global_load_lds_dwordx4 v[236:237], off
	s_mov_b32 m0, s57
	v_lshl_add_u64 v[248:249], s[44:45], 0, v[96:97]
	global_load_lds_dwordx4 v[246:247], off
	s_mov_b32 m0, s60
	s_nop 0
	global_load_lds_dwordx4 v[248:249], off
	s_waitcnt vmcnt(8)
	s_waitcnt lgkmcnt(0)
	s_barrier
	s_setprio 1
	s_waitcnt lgkmcnt(0)
	v_mfma_f32_16x16x32_bf16 v[60:63], v[142:145], v[196:199], 0
	v_mfma_f32_16x16x32_bf16 v[56:59], v[162:165], v[196:199], 0
	v_mfma_f32_16x16x32_bf16 v[44:47], v[142:145], v[204:207], 0
	v_mfma_f32_16x16x32_bf16 v[40:43], v[162:165], v[204:207], 0
	v_mfma_f32_16x16x32_bf16 v[28:31], v[142:145], v[212:215], 0
	v_mfma_f32_16x16x32_bf16 v[24:27], v[162:165], v[212:215], 0
	v_mfma_f32_16x16x32_bf16 v[12:15], v[142:145], v[238:241], 0
	v_mfma_f32_16x16x32_bf16 v[8:11], v[162:165], v[238:241], 0
	v_mfma_f32_16x16x32_bf16 v[60:63], v[158:161], v[200:203], v[60:63]
	v_mfma_f32_16x16x32_bf16 v[56:59], v[166:169], v[200:203], v[56:59]
	v_mfma_f32_16x16x32_bf16 v[44:47], v[158:161], v[208:211], v[44:47]
	v_mfma_f32_16x16x32_bf16 v[40:43], v[166:169], v[208:211], v[40:43]
	v_mfma_f32_16x16x32_bf16 v[28:31], v[158:161], v[216:219], v[28:31]
	v_mfma_f32_16x16x32_bf16 v[24:27], v[166:169], v[216:219], v[24:27]
	v_mfma_f32_16x16x32_bf16 v[12:15], v[158:161], v[242:245], v[12:15]
	v_mfma_f32_16x16x32_bf16 v[8:11], v[166:169], v[242:245], v[8:11]
	s_setprio 0
	s_setprio 1
	v_mfma_f32_16x16x32_bf16 v[52:55], v[170:173], v[196:199], 0
	v_mfma_f32_16x16x32_bf16 v[48:51], v[188:191], v[196:199], 0
	v_mfma_f32_16x16x32_bf16 v[36:39], v[170:173], v[204:207], 0
	v_mfma_f32_16x16x32_bf16 v[32:35], v[188:191], v[204:207], 0
	v_mfma_f32_16x16x32_bf16 v[20:23], v[170:173], v[212:215], 0
	v_mfma_f32_16x16x32_bf16 v[16:19], v[188:191], v[212:215], 0
	v_mfma_f32_16x16x32_bf16 v[4:7], v[170:173], v[238:241], 0
	v_mfma_f32_16x16x32_bf16 v[0:3], v[188:191], v[238:241], 0
	v_mfma_f32_16x16x32_bf16 v[52:55], v[174:177], v[200:203], v[52:55]
	v_mfma_f32_16x16x32_bf16 v[48:51], v[192:195], v[200:203], v[48:51]
	v_mfma_f32_16x16x32_bf16 v[36:39], v[174:177], v[208:211], v[36:39]
	v_mfma_f32_16x16x32_bf16 v[32:35], v[192:195], v[208:211], v[32:35]
	v_mfma_f32_16x16x32_bf16 v[20:23], v[174:177], v[216:219], v[20:23]
	v_mfma_f32_16x16x32_bf16 v[16:19], v[192:195], v[216:219], v[16:19]
	v_mfma_f32_16x16x32_bf16 v[4:7], v[174:177], v[242:245], v[4:7]
	v_mfma_f32_16x16x32_bf16 v[0:3], v[192:195], v[242:245], v[0:3]
	s_setprio 0
	s_barrier
	s_add_i32 s20, 0, 0x18000
	v_add_u32_e32 v98, s20, v156
	s_add_i32 s21, 0, 0x1c000
	ds_read_b128 v[142:145], v98
	ds_read_b128 v[158:161], v98 offset:1024
	ds_read_b128 v[162:165], v98 offset:2048
	ds_read_b128 v[166:169], v98 offset:3072
	v_add_u32_e32 v98, s21, v156
	ds_read_b128 v[170:173], v98
	ds_read_b128 v[174:177], v98 offset:1024
	ds_read_b128 v[188:191], v98 offset:2048
	ds_read_b128 v[192:195], v98 offset:3072
	s_add_u32 s44, s44, s6
	s_addc_u32 s45, s45, s7
	s_mov_b32 m0, s61
	v_lshl_add_u64 v[228:229], s[44:45], 0, v[132:133]
	ds_read_b128 v[196:199], v157 offset:32768
	ds_read_b128 v[200:203], v157 offset:33792
	ds_read_b128 v[204:207], v157 offset:34816
	ds_read_b128 v[208:211], v157 offset:35840
	ds_read_b128 v[212:215], v157 offset:36864
	ds_read_b128 v[216:219], v157 offset:37888
	ds_read_b128 v[238:241], v157 offset:38912
	ds_read_b128 v[242:245], v157 offset:39936
	global_load_lds_dwordx4 v[228:229], off
	v_lshl_add_u64 v[228:229], s[44:45], 0, v[96:97]
	s_mov_b32 m0, s62
	s_nop 0
	global_load_lds_dwordx4 v[228:229], off
	s_waitcnt vmcnt(8)
	s_waitcnt lgkmcnt(0)
	s_barrier
	s_setprio 1
	s_waitcnt lgkmcnt(0)
	v_mfma_f32_16x16x32_bf16 v[128:131], v[142:145], v[196:199], v[128:131]
	v_mfma_f32_16x16x32_bf16 v[124:127], v[162:165], v[196:199], v[124:127]
	v_mfma_f32_16x16x32_bf16 v[112:115], v[142:145], v[204:207], v[112:115]
	v_mfma_f32_16x16x32_bf16 v[108:111], v[162:165], v[204:207], v[108:111]
	v_mfma_f32_16x16x32_bf16 v[92:95], v[142:145], v[212:215], v[92:95]
	v_mfma_f32_16x16x32_bf16 v[88:91], v[162:165], v[212:215], v[88:91]
	v_mfma_f32_16x16x32_bf16 v[76:79], v[142:145], v[238:241], v[76:79]
	v_mfma_f32_16x16x32_bf16 v[72:75], v[162:165], v[238:241], v[72:75]
	v_mfma_f32_16x16x32_bf16 v[128:131], v[158:161], v[200:203], v[128:131]
	v_mfma_f32_16x16x32_bf16 v[124:127], v[166:169], v[200:203], v[124:127]
	v_mfma_f32_16x16x32_bf16 v[112:115], v[158:161], v[208:211], v[112:115]
	v_mfma_f32_16x16x32_bf16 v[108:111], v[166:169], v[208:211], v[108:111]
	v_mfma_f32_16x16x32_bf16 v[92:95], v[158:161], v[216:219], v[92:95]
	v_mfma_f32_16x16x32_bf16 v[88:91], v[166:169], v[216:219], v[88:91]
	v_mfma_f32_16x16x32_bf16 v[76:79], v[158:161], v[242:245], v[76:79]
	v_mfma_f32_16x16x32_bf16 v[72:75], v[166:169], v[242:245], v[72:75]
	s_setprio 0
	s_setprio 1
	v_mfma_f32_16x16x32_bf16 v[120:123], v[170:173], v[196:199], v[120:123]
	v_mfma_f32_16x16x32_bf16 v[116:119], v[188:191], v[196:199], v[116:119]
	v_mfma_f32_16x16x32_bf16 v[104:107], v[170:173], v[204:207], v[104:107]
	v_mfma_f32_16x16x32_bf16 v[100:103], v[188:191], v[204:207], v[100:103]
	v_mfma_f32_16x16x32_bf16 v[84:87], v[170:173], v[212:215], v[84:87]
	v_mfma_f32_16x16x32_bf16 v[80:83], v[188:191], v[212:215], v[80:83]
	v_mfma_f32_16x16x32_bf16 v[68:71], v[170:173], v[238:241], v[68:71]
	v_mfma_f32_16x16x32_bf16 v[64:67], v[188:191], v[238:241], v[64:67]
	v_mfma_f32_16x16x32_bf16 v[120:123], v[174:177], v[200:203], v[120:123]
	v_mfma_f32_16x16x32_bf16 v[116:119], v[192:195], v[200:203], v[116:119]
	v_mfma_f32_16x16x32_bf16 v[104:107], v[174:177], v[208:211], v[104:107]
	v_mfma_f32_16x16x32_bf16 v[100:103], v[192:195], v[208:211], v[100:103]
	v_mfma_f32_16x16x32_bf16 v[84:87], v[174:177], v[216:219], v[84:87]
	v_mfma_f32_16x16x32_bf16 v[80:83], v[192:195], v[216:219], v[80:83]
	v_mfma_f32_16x16x32_bf16 v[68:71], v[174:177], v[242:245], v[68:71]
	v_mfma_f32_16x16x32_bf16 v[64:67], v[192:195], v[242:245], v[64:67]
	s_setprio 0
	s_barrier
	s_add_i32 s20, s20, s56
	v_lshl_add_u64 v[178:179], v[178:179], 0, s[30:31]
	s_mov_b32 m0, s20
	ds_read_b128 v[196:199], v157 offset:49152
	ds_read_b128 v[200:203], v157 offset:50176
	ds_read_b128 v[204:207], v157 offset:51200
	ds_read_b128 v[208:211], v157 offset:52224
	ds_read_b128 v[212:215], v157 offset:53248
	ds_read_b128 v[216:219], v157 offset:54272
	ds_read_b128 v[238:241], v157 offset:55296
	ds_read_b128 v[242:245], v157 offset:56320
	global_load_lds_dwordx4 v[178:179], off
	v_lshl_add_u64 v[178:179], v[220:221], 0, s[30:31]
	s_add_i32 m0, s20, 0x2000
	s_add_i32 s20, s21, s56
	global_load_lds_dwordx4 v[178:179], off
	v_lshl_add_u64 v[178:179], v[234:235], 0, s[30:31]
	s_mov_b32 m0, s20
	s_nop 0
	global_load_lds_dwordx4 v[178:179], off
	v_lshl_add_u64 v[178:179], v[236:237], 0, s[30:31]
	s_add_i32 m0, s20, 0x2000
	s_nop 0
	global_load_lds_dwordx4 v[178:179], off
	v_lshl_add_u64 v[178:179], v[246:247], 0, s[30:31]
	s_mov_b32 m0, s63
	s_nop 0
	global_load_lds_dwordx4 v[178:179], off
	v_lshl_add_u64 v[178:179], v[248:249], 0, s[30:31]
	s_mov_b32 m0, s64
	s_nop 0
	global_load_lds_dwordx4 v[178:179], off
	s_waitcnt vmcnt(8)
	s_waitcnt lgkmcnt(0)
	s_barrier
	s_setprio 1
	s_waitcnt lgkmcnt(0)
	v_mfma_f32_16x16x32_bf16 v[60:63], v[142:145], v[196:199], v[60:63]
	v_mfma_f32_16x16x32_bf16 v[56:59], v[162:165], v[196:199], v[56:59]
	v_mfma_f32_16x16x32_bf16 v[44:47], v[142:145], v[204:207], v[44:47]
	v_mfma_f32_16x16x32_bf16 v[40:43], v[162:165], v[204:207], v[40:43]
	v_mfma_f32_16x16x32_bf16 v[28:31], v[142:145], v[212:215], v[28:31]
	v_mfma_f32_16x16x32_bf16 v[24:27], v[162:165], v[212:215], v[24:27]
	v_mfma_f32_16x16x32_bf16 v[12:15], v[142:145], v[238:241], v[12:15]
	v_mfma_f32_16x16x32_bf16 v[8:11], v[162:165], v[238:241], v[8:11]
	v_mfma_f32_16x16x32_bf16 v[60:63], v[158:161], v[200:203], v[60:63]
	v_mfma_f32_16x16x32_bf16 v[56:59], v[166:169], v[200:203], v[56:59]
	v_mfma_f32_16x16x32_bf16 v[44:47], v[158:161], v[208:211], v[44:47]
	v_mfma_f32_16x16x32_bf16 v[40:43], v[166:169], v[208:211], v[40:43]
	v_mfma_f32_16x16x32_bf16 v[28:31], v[158:161], v[216:219], v[28:31]
	v_mfma_f32_16x16x32_bf16 v[24:27], v[166:169], v[216:219], v[24:27]
	v_mfma_f32_16x16x32_bf16 v[12:15], v[158:161], v[242:245], v[12:15]
	v_mfma_f32_16x16x32_bf16 v[8:11], v[166:169], v[242:245], v[8:11]
	s_setprio 0
	s_setprio 1
	v_mfma_f32_16x16x32_bf16 v[52:55], v[170:173], v[196:199], v[52:55]
	v_mfma_f32_16x16x32_bf16 v[48:51], v[188:191], v[196:199], v[48:51]
	v_mfma_f32_16x16x32_bf16 v[36:39], v[170:173], v[204:207], v[36:39]
	v_mfma_f32_16x16x32_bf16 v[32:35], v[188:191], v[204:207], v[32:35]
	v_mfma_f32_16x16x32_bf16 v[20:23], v[170:173], v[212:215], v[20:23]
	v_mfma_f32_16x16x32_bf16 v[16:19], v[188:191], v[212:215], v[16:19]
	v_mfma_f32_16x16x32_bf16 v[4:7], v[170:173], v[238:241], v[4:7]
	v_mfma_f32_16x16x32_bf16 v[0:3], v[188:191], v[238:241], v[0:3]
	v_mfma_f32_16x16x32_bf16 v[52:55], v[174:177], v[200:203], v[52:55]
	v_mfma_f32_16x16x32_bf16 v[48:51], v[192:195], v[200:203], v[48:51]
	v_mfma_f32_16x16x32_bf16 v[36:39], v[174:177], v[208:211], v[36:39]
	v_mfma_f32_16x16x32_bf16 v[32:35], v[192:195], v[208:211], v[32:35]
	v_mfma_f32_16x16x32_bf16 v[20:23], v[174:177], v[216:219], v[20:23]
	v_mfma_f32_16x16x32_bf16 v[16:19], v[192:195], v[216:219], v[16:19]
	v_mfma_f32_16x16x32_bf16 v[4:7], v[174:177], v[242:245], v[4:7]
	v_mfma_f32_16x16x32_bf16 v[0:3], v[192:195], v[242:245], v[0:3]
	s_setprio 0
	s_barrier
	s_add_u32 s25, s25, 0x100
	s_addc_u32 s26, s26, 0
	s_add_u32 s42, s42, 0x100
	s_addc_u32 s43, s43, 0
	s_cmp_ge_i32 s46, s65
	s_mov_b32 s27, s46
	s_cbranch_scc1 .Lpeel_exit_uq

.Lpeel_exit_uq:
.LBB0_617:
	s_and_b64 vcc, exec, s[14:15]
	s_cbranch_vccz .LBB0_619
	s_barrier

.Lnz_ukv:
	s_add_u32 s56, s42, 0x100
	s_addc_u32 s57, s43, 0
	s_add_u32 s40, s44, 0x80
	s_addc_u32 s41, s45, 0
	s_mov_b32 s42, 0
	s_add_i32 s44, s42, 2
	s_add_u32 s20, s40, 0x80
	s_addc_u32 s21, s41, 0
	s_add_i32 s23, 0, 0x10000
	s_cmp_eq_u32 s50, s42
	s_cselect_b32 s43, s17, s21
	s_cselect_b32 s42, s16, s20
	s_cselect_b32 s61, s19, s57
	s_cselect_b32 s60, s18, s56
	s_add_i32 s20, 0, 0x14000
	v_add_u32_e32 v150, s23, v155
	v_add_u32_e32 v157, s20, v155
	ds_read_b128 v[138:141], v150
	ds_read_b128 v[142:145], v150 offset:1024
	ds_read_b128 v[146:149], v150 offset:2048
	ds_read_b128 v[150:153], v150 offset:3072
	ds_read_b128 v[158:161], v157
	ds_read_b128 v[162:165], v157 offset:1024
	ds_read_b128 v[166:169], v157 offset:2048
	ds_read_b128 v[170:173], v157 offset:3072
	v_lshl_add_u64 v[178:179], s[40:41], 0, v[136:137]
	s_add_i32 m0, s26, 0xc000
	ds_read_b128 v[174:177], v156
	ds_read_b128 v[188:191], v156 offset:1024
	ds_read_b128 v[192:195], v156 offset:2048
	ds_read_b128 v[196:199], v156 offset:3072
	ds_read_b128 v[200:203], v156 offset:4096
	ds_read_b128 v[204:207], v156 offset:5120
	ds_read_b128 v[208:211], v156 offset:6144
	ds_read_b128 v[212:215], v156 offset:7168
	global_load_lds_dwordx4 v[178:179], off
	v_lshl_add_u64 v[178:179], s[40:41], 0, v[134:135]
	s_add_i32 m0, s26, 0xe000
	s_nop 0
	global_load_lds_dwordx4 v[178:179], off
	s_waitcnt vmcnt(8)
	s_waitcnt lgkmcnt(0)
	s_barrier
	s_setprio 1
	s_waitcnt lgkmcnt(0)
	v_mfma_f32_16x16x32_bf16 v[128:131], v[138:141], v[174:177], 0
	v_mfma_f32_16x16x32_bf16 v[124:127], v[146:149], v[174:177], 0
	v_mfma_f32_16x16x32_bf16 v[112:115], v[138:141], v[192:195], 0
	v_mfma_f32_16x16x32_bf16 v[108:111], v[146:149], v[192:195], 0
	v_mfma_f32_16x16x32_bf16 v[92:95], v[138:141], v[200:203], 0
	v_mfma_f32_16x16x32_bf16 v[88:91], v[146:149], v[200:203], 0
	v_mfma_f32_16x16x32_bf16 v[76:79], v[138:141], v[208:211], 0
	v_mfma_f32_16x16x32_bf16 v[72:75], v[146:149], v[208:211], 0
	v_mfma_f32_16x16x32_bf16 v[128:131], v[142:145], v[188:191], v[128:131]
	v_mfma_f32_16x16x32_bf16 v[124:127], v[150:153], v[188:191], v[124:127]
	v_mfma_f32_16x16x32_bf16 v[112:115], v[142:145], v[196:199], v[112:115]
	v_mfma_f32_16x16x32_bf16 v[108:111], v[150:153], v[196:199], v[108:111]
	v_mfma_f32_16x16x32_bf16 v[92:95], v[142:145], v[204:207], v[92:95]
	v_mfma_f32_16x16x32_bf16 v[88:91], v[150:153], v[204:207], v[88:91]
	v_mfma_f32_16x16x32_bf16 v[76:79], v[142:145], v[212:215], v[76:79]
	v_mfma_f32_16x16x32_bf16 v[72:75], v[150:153], v[212:215], v[72:75]
	s_setprio 0
	s_setprio 1
	v_mfma_f32_16x16x32_bf16 v[120:123], v[158:161], v[174:177], 0
	v_mfma_f32_16x16x32_bf16 v[116:119], v[166:169], v[174:177], 0
	v_mfma_f32_16x16x32_bf16 v[104:107], v[158:161], v[192:195], 0
	v_mfma_f32_16x16x32_bf16 v[100:103], v[166:169], v[192:195], 0
	v_mfma_f32_16x16x32_bf16 v[84:87], v[158:161], v[200:203], 0
	v_mfma_f32_16x16x32_bf16 v[80:83], v[166:169], v[200:203], 0
	v_mfma_f32_16x16x32_bf16 v[68:71], v[158:161], v[208:211], 0
	v_mfma_f32_16x16x32_bf16 v[64:67], v[166:169], v[208:211], 0
	v_mfma_f32_16x16x32_bf16 v[120:123], v[162:165], v[188:191], v[120:123]
	v_mfma_f32_16x16x32_bf16 v[116:119], v[170:173], v[188:191], v[116:119]
	v_mfma_f32_16x16x32_bf16 v[104:107], v[162:165], v[196:199], v[104:107]
	v_mfma_f32_16x16x32_bf16 v[100:103], v[170:173], v[196:199], v[100:103]
	v_mfma_f32_16x16x32_bf16 v[84:87], v[162:165], v[204:207], v[84:87]
	v_mfma_f32_16x16x32_bf16 v[80:83], v[170:173], v[204:207], v[80:83]
	v_mfma_f32_16x16x32_bf16 v[68:71], v[162:165], v[212:215], v[68:71]
	v_mfma_f32_16x16x32_bf16 v[64:67], v[170:173], v[212:215], v[64:67]
	s_setprio 0
	s_barrier
	s_add_i32 s21, s23, s25
	v_lshl_add_u64 v[178:179], s[60:61], 0, v[132:133]
	s_mov_b32 m0, s21
	ds_read_b128 v[174:177], v156 offset:16384
	ds_read_b128 v[188:191], v156 offset:17408
	ds_read_b128 v[192:195], v156 offset:18432
	ds_read_b128 v[196:199], v156 offset:19456
	ds_read_b128 v[200:203], v156 offset:20480
	ds_read_b128 v[204:207], v156 offset:21504
	ds_read_b128 v[208:211], v156 offset:22528
	ds_read_b128 v[212:215], v156 offset:23552
	global_load_lds_dwordx4 v[178:179], off
	s_add_i32 m0, s21, 0x2000
	v_lshl_add_u64 v[216:217], s[60:61], 0, v[96:97]
	s_add_u32 s60, s60, s6
	s_addc_u32 s61, s61, s7
	s_add_i32 s20, s20, s25
	global_load_lds_dwordx4 v[216:217], off
	v_lshl_add_u64 v[218:219], s[60:61], 0, v[132:133]
	s_mov_b32 m0, s20
	v_lshl_add_u64 v[220:221], s[60:61], 0, v[96:97]
	global_load_lds_dwordx4 v[218:219], off
	s_add_i32 m0, s20, 0x2000
	v_lshl_add_u64 v[228:229], s[42:43], 0, v[132:133]
	global_load_lds_dwordx4 v[220:221], off
	s_mov_b32 m0, s26
	v_lshl_add_u64 v[234:235], s[42:43], 0, v[96:97]
	global_load_lds_dwordx4 v[228:229], off
	s_mov_b32 m0, s27
	s_nop 0
	global_load_lds_dwordx4 v[234:235], off
	s_waitcnt vmcnt(8)
	s_waitcnt lgkmcnt(0)
	s_barrier
	s_setprio 1
	s_waitcnt lgkmcnt(0)
	v_mfma_f32_16x16x32_bf16 v[60:63], v[138:141], v[174:177], 0
	v_mfma_f32_16x16x32_bf16 v[56:59], v[146:149], v[174:177], 0
	v_mfma_f32_16x16x32_bf16 v[44:47], v[138:141], v[192:195], 0
	v_mfma_f32_16x16x32_bf16 v[40:43], v[146:149], v[192:195], 0
	v_mfma_f32_16x16x32_bf16 v[28:31], v[138:141], v[200:203], 0
	v_mfma_f32_16x16x32_bf16 v[24:27], v[146:149], v[200:203], 0
	v_mfma_f32_16x16x32_bf16 v[12:15], v[138:141], v[208:211], 0
	v_mfma_f32_16x16x32_bf16 v[8:11], v[146:149], v[208:211], 0
	v_mfma_f32_16x16x32_bf16 v[60:63], v[142:145], v[188:191], v[60:63]
	v_mfma_f32_16x16x32_bf16 v[56:59], v[150:153], v[188:191], v[56:59]
	v_mfma_f32_16x16x32_bf16 v[44:47], v[142:145], v[196:199], v[44:47]
	v_mfma_f32_16x16x32_bf16 v[40:43], v[150:153], v[196:199], v[40:43]
	v_mfma_f32_16x16x32_bf16 v[28:31], v[142:145], v[204:207], v[28:31]
	v_mfma_f32_16x16x32_bf16 v[24:27], v[150:153], v[204:207], v[24:27]
	v_mfma_f32_16x16x32_bf16 v[12:15], v[142:145], v[212:215], v[12:15]
	v_mfma_f32_16x16x32_bf16 v[8:11], v[150:153], v[212:215], v[8:11]
	s_setprio 0
	s_setprio 1
	v_mfma_f32_16x16x32_bf16 v[52:55], v[158:161], v[174:177], 0
	v_mfma_f32_16x16x32_bf16 v[48:51], v[166:169], v[174:177], 0
	v_mfma_f32_16x16x32_bf16 v[36:39], v[158:161], v[192:195], 0
	v_mfma_f32_16x16x32_bf16 v[32:35], v[166:169], v[192:195], 0
	v_mfma_f32_16x16x32_bf16 v[20:23], v[158:161], v[200:203], 0
	v_mfma_f32_16x16x32_bf16 v[16:19], v[166:169], v[200:203], 0
	v_mfma_f32_16x16x32_bf16 v[4:7], v[158:161], v[208:211], 0
	v_mfma_f32_16x16x32_bf16 v[0:3], v[166:169], v[208:211], 0
	v_mfma_f32_16x16x32_bf16 v[52:55], v[162:165], v[188:191], v[52:55]
	v_mfma_f32_16x16x32_bf16 v[48:51], v[170:173], v[188:191], v[48:51]
	v_mfma_f32_16x16x32_bf16 v[36:39], v[162:165], v[196:199], v[36:39]
	v_mfma_f32_16x16x32_bf16 v[32:35], v[170:173], v[196:199], v[32:35]
	v_mfma_f32_16x16x32_bf16 v[20:23], v[162:165], v[204:207], v[20:23]
	v_mfma_f32_16x16x32_bf16 v[16:19], v[170:173], v[204:207], v[16:19]
	v_mfma_f32_16x16x32_bf16 v[4:7], v[162:165], v[212:215], v[4:7]
	v_mfma_f32_16x16x32_bf16 v[0:3], v[170:173], v[212:215], v[0:3]
	s_setprio 0
	s_barrier
	s_add_i32 s20, 0, 0x18000
	s_add_i32 s21, 0, 0x1c000
	v_add_u32_e32 v150, s20, v155
	v_add_u32_e32 v157, s21, v155
	ds_read_b128 v[138:141], v150
	ds_read_b128 v[142:145], v150 offset:1024
	ds_read_b128 v[146:149], v150 offset:2048
	ds_read_b128 v[150:153], v150 offset:3072
	ds_read_b128 v[158:161], v157
	ds_read_b128 v[162:165], v157 offset:1024
	ds_read_b128 v[166:169], v157 offset:2048
	ds_read_b128 v[170:173], v157 offset:3072
	s_add_u32 s42, s42, s6
	s_addc_u32 s43, s43, s7
	s_mov_b32 m0, s36
	v_lshl_add_u64 v[236:237], s[42:43], 0, v[132:133]
	ds_read_b128 v[174:177], v156 offset:32768
	ds_read_b128 v[188:191], v156 offset:33792
	ds_read_b128 v[192:195], v156 offset:34816
	ds_read_b128 v[196:199], v156 offset:35840
	ds_read_b128 v[200:203], v156 offset:36864
	ds_read_b128 v[204:207], v156 offset:37888
	ds_read_b128 v[208:211], v156 offset:38912
	ds_read_b128 v[212:215], v156 offset:39936
	global_load_lds_dwordx4 v[236:237], off
	v_lshl_add_u64 v[236:237], s[42:43], 0, v[96:97]
	s_mov_b32 m0, s37
	s_nop 0
	global_load_lds_dwordx4 v[236:237], off
	s_waitcnt vmcnt(8)
	s_waitcnt lgkmcnt(0)
	s_barrier
	s_setprio 1
	s_waitcnt lgkmcnt(0)
	v_mfma_f32_16x16x32_bf16 v[128:131], v[138:141], v[174:177], v[128:131]
	v_mfma_f32_16x16x32_bf16 v[124:127], v[146:149], v[174:177], v[124:127]
	v_mfma_f32_16x16x32_bf16 v[112:115], v[138:141], v[192:195], v[112:115]
	v_mfma_f32_16x16x32_bf16 v[108:111], v[146:149], v[192:195], v[108:111]
	v_mfma_f32_16x16x32_bf16 v[92:95], v[138:141], v[200:203], v[92:95]
	v_mfma_f32_16x16x32_bf16 v[88:91], v[146:149], v[200:203], v[88:91]
	v_mfma_f32_16x16x32_bf16 v[76:79], v[138:141], v[208:211], v[76:79]
	v_mfma_f32_16x16x32_bf16 v[72:75], v[146:149], v[208:211], v[72:75]
	v_mfma_f32_16x16x32_bf16 v[128:131], v[142:145], v[188:191], v[128:131]
	v_mfma_f32_16x16x32_bf16 v[124:127], v[150:153], v[188:191], v[124:127]
	v_mfma_f32_16x16x32_bf16 v[112:115], v[142:145], v[196:199], v[112:115]
	v_mfma_f32_16x16x32_bf16 v[108:111], v[150:153], v[196:199], v[108:111]
	v_mfma_f32_16x16x32_bf16 v[92:95], v[142:145], v[204:207], v[92:95]
	v_mfma_f32_16x16x32_bf16 v[88:91], v[150:153], v[204:207], v[88:91]
	v_mfma_f32_16x16x32_bf16 v[76:79], v[142:145], v[212:215], v[76:79]
	v_mfma_f32_16x16x32_bf16 v[72:75], v[150:153], v[212:215], v[72:75]
	s_setprio 0
	s_setprio 1
	v_mfma_f32_16x16x32_bf16 v[120:123], v[158:161], v[174:177], v[120:123]
	v_mfma_f32_16x16x32_bf16 v[116:119], v[166:169], v[174:177], v[116:119]
	v_mfma_f32_16x16x32_bf16 v[104:107], v[158:161], v[192:195], v[104:107]
	v_mfma_f32_16x16x32_bf16 v[100:103], v[166:169], v[192:195], v[100:103]
	v_mfma_f32_16x16x32_bf16 v[84:87], v[158:161], v[200:203], v[84:87]
	v_mfma_f32_16x16x32_bf16 v[80:83], v[166:169], v[200:203], v[80:83]
	v_mfma_f32_16x16x32_bf16 v[68:71], v[158:161], v[208:211], v[68:71]
	v_mfma_f32_16x16x32_bf16 v[64:67], v[166:169], v[208:211], v[64:67]
	v_mfma_f32_16x16x32_bf16 v[120:123], v[162:165], v[188:191], v[120:123]
	v_mfma_f32_16x16x32_bf16 v[116:119], v[170:173], v[188:191], v[116:119]
	v_mfma_f32_16x16x32_bf16 v[104:107], v[162:165], v[196:199], v[104:107]
	v_mfma_f32_16x16x32_bf16 v[100:103], v[170:173], v[196:199], v[100:103]
	v_mfma_f32_16x16x32_bf16 v[84:87], v[162:165], v[204:207], v[84:87]
	v_mfma_f32_16x16x32_bf16 v[80:83], v[170:173], v[204:207], v[80:83]
	v_mfma_f32_16x16x32_bf16 v[68:71], v[162:165], v[212:215], v[68:71]
	v_mfma_f32_16x16x32_bf16 v[64:67], v[170:173], v[212:215], v[64:67]
	s_setprio 0
	s_barrier
	s_add_i32 s20, s20, s25
	v_lshl_add_u64 v[178:179], v[178:179], 0, s[30:31]
	s_mov_b32 m0, s20
	ds_read_b128 v[174:177], v156 offset:49152
	ds_read_b128 v[188:191], v156 offset:50176
	ds_read_b128 v[192:195], v156 offset:51200
	ds_read_b128 v[196:199], v156 offset:52224
	ds_read_b128 v[200:203], v156 offset:53248
	ds_read_b128 v[204:207], v156 offset:54272
	ds_read_b128 v[208:211], v156 offset:55296
	ds_read_b128 v[212:215], v156 offset:56320
	global_load_lds_dwordx4 v[178:179], off
	v_lshl_add_u64 v[178:179], v[216:217], 0, s[30:31]
	s_add_i32 m0, s20, 0x2000
	s_add_i32 s20, s21, s25
	global_load_lds_dwordx4 v[178:179], off
	v_lshl_add_u64 v[178:179], v[218:219], 0, s[30:31]
	s_mov_b32 m0, s20
	s_nop 0
	global_load_lds_dwordx4 v[178:179], off
	v_lshl_add_u64 v[178:179], v[220:221], 0, s[30:31]
	s_add_i32 m0, s20, 0x2000
	s_nop 0
	global_load_lds_dwordx4 v[178:179], off
	v_lshl_add_u64 v[178:179], v[228:229], 0, s[30:31]
	s_mov_b32 m0, s46
	s_nop 0
	global_load_lds_dwordx4 v[178:179], off
	v_lshl_add_u64 v[178:179], v[234:235], 0, s[30:31]
	s_mov_b32 m0, s47
	s_nop 0
	global_load_lds_dwordx4 v[178:179], off
	s_waitcnt vmcnt(8)
	s_waitcnt lgkmcnt(0)
	s_barrier
	s_setprio 1
	s_waitcnt lgkmcnt(0)
	v_mfma_f32_16x16x32_bf16 v[60:63], v[138:141], v[174:177], v[60:63]
	v_mfma_f32_16x16x32_bf16 v[56:59], v[146:149], v[174:177], v[56:59]
	v_mfma_f32_16x16x32_bf16 v[44:47], v[138:141], v[192:195], v[44:47]
	v_mfma_f32_16x16x32_bf16 v[40:43], v[146:149], v[192:195], v[40:43]
	v_mfma_f32_16x16x32_bf16 v[28:31], v[138:141], v[200:203], v[28:31]
	v_mfma_f32_16x16x32_bf16 v[24:27], v[146:149], v[200:203], v[24:27]
	v_mfma_f32_16x16x32_bf16 v[12:15], v[138:141], v[208:211], v[12:15]
	v_mfma_f32_16x16x32_bf16 v[8:11], v[146:149], v[208:211], v[8:11]
	v_mfma_f32_16x16x32_bf16 v[60:63], v[142:145], v[188:191], v[60:63]
	v_mfma_f32_16x16x32_bf16 v[56:59], v[150:153], v[188:191], v[56:59]
	v_mfma_f32_16x16x32_bf16 v[44:47], v[142:145], v[196:199], v[44:47]
	v_mfma_f32_16x16x32_bf16 v[40:43], v[150:153], v[196:199], v[40:43]
	v_mfma_f32_16x16x32_bf16 v[28:31], v[142:145], v[204:207], v[28:31]
	v_mfma_f32_16x16x32_bf16 v[24:27], v[150:153], v[204:207], v[24:27]
	v_mfma_f32_16x16x32_bf16 v[12:15], v[142:145], v[212:215], v[12:15]
	v_mfma_f32_16x16x32_bf16 v[8:11], v[150:153], v[212:215], v[8:11]
	s_setprio 0
	s_setprio 1
	v_mfma_f32_16x16x32_bf16 v[52:55], v[158:161], v[174:177], v[52:55]
	v_mfma_f32_16x16x32_bf16 v[48:51], v[166:169], v[174:177], v[48:51]
	v_mfma_f32_16x16x32_bf16 v[36:39], v[158:161], v[192:195], v[36:39]
	v_mfma_f32_16x16x32_bf16 v[32:35], v[166:169], v[192:195], v[32:35]
	v_mfma_f32_16x16x32_bf16 v[20:23], v[158:161], v[200:203], v[20:23]
	v_mfma_f32_16x16x32_bf16 v[16:19], v[166:169], v[200:203], v[16:19]
	v_mfma_f32_16x16x32_bf16 v[4:7], v[158:161], v[208:211], v[4:7]
	v_mfma_f32_16x16x32_bf16 v[0:3], v[166:169], v[208:211], v[0:3]
	v_mfma_f32_16x16x32_bf16 v[52:55], v[162:165], v[188:191], v[52:55]
	v_mfma_f32_16x16x32_bf16 v[48:51], v[170:173], v[188:191], v[48:51]
	v_mfma_f32_16x16x32_bf16 v[36:39], v[162:165], v[196:199], v[36:39]
	v_mfma_f32_16x16x32_bf16 v[32:35], v[170:173], v[196:199], v[32:35]
	v_mfma_f32_16x16x32_bf16 v[20:23], v[162:165], v[204:207], v[20:23]
	v_mfma_f32_16x16x32_bf16 v[16:19], v[170:173], v[204:207], v[16:19]
	v_mfma_f32_16x16x32_bf16 v[4:7], v[162:165], v[212:215], v[4:7]
	v_mfma_f32_16x16x32_bf16 v[0:3], v[170:173], v[212:215], v[0:3]
	s_setprio 0
	s_barrier
	s_add_u32 s56, s56, 0x100
	s_addc_u32 s57, s57, 0
	s_add_u32 s40, s40, 0x100
	s_addc_u32 s41, s41, 0
	s_cmp_ge_i32 s44, s48
	s_mov_b32 s42, s44
	s_cbranch_scc1 .Lpeel_exit_ukv

.LBB0_983:
	s_andn2_b64 vcc, exec, s[6:7]
	s_cbranch_vccz .Lnz_part
	v_mov_b32_e32 v131, 0
	v_mov_b32_e32 v130, v131
	v_mov_b32_e32 v129, v131
	v_mov_b32_e32 v128, v131
	v_mov_b32_e32 v127, v131
	v_mov_b32_e32 v126, v131
	v_mov_b32_e32 v125, v131
	v_mov_b32_e32 v124, v131
	v_mov_b32_e32 v115, v131
	v_mov_b32_e32 v114, v131
	v_mov_b32_e32 v113, v131
	v_mov_b32_e32 v112, v131
	v_mov_b32_e32 v111, v131
	v_mov_b32_e32 v110, v131
	v_mov_b32_e32 v109, v131
	v_mov_b32_e32 v108, v131
	v_mov_b32_e32 v95, v131
	v_mov_b32_e32 v94, v131
	v_mov_b32_e32 v93, v131
	v_mov_b32_e32 v92, v131
	v_mov_b32_e32 v91, v131
	v_mov_b32_e32 v90, v131
	v_mov_b32_e32 v89, v131
	v_mov_b32_e32 v88, v131
	v_mov_b32_e32 v79, v131
	v_mov_b32_e32 v78, v131
	v_mov_b32_e32 v77, v131
	v_mov_b32_e32 v76, v131
	v_mov_b32_e32 v75, v131
	v_mov_b32_e32 v74, v131
	v_mov_b32_e32 v73, v131
	v_mov_b32_e32 v72, v131
	v_mov_b32_e32 v123, v131
	v_mov_b32_e32 v122, v131
	v_mov_b32_e32 v121, v131
	v_mov_b32_e32 v120, v131
	v_mov_b32_e32 v119, v131
	v_mov_b32_e32 v118, v131
	v_mov_b32_e32 v117, v131
	v_mov_b32_e32 v116, v131
	v_mov_b32_e32 v107, v131
	v_mov_b32_e32 v106, v131
	v_mov_b32_e32 v105, v131
	v_mov_b32_e32 v104, v131
	v_mov_b32_e32 v103, v131
	v_mov_b32_e32 v102, v131
	v_mov_b32_e32 v101, v131
	v_mov_b32_e32 v100, v131
	v_mov_b32_e32 v87, v131
	v_mov_b32_e32 v86, v131
	v_mov_b32_e32 v85, v131
	v_mov_b32_e32 v84, v131
	v_mov_b32_e32 v83, v131
	v_mov_b32_e32 v82, v131
	v_mov_b32_e32 v81, v131
	v_mov_b32_e32 v80, v131
	v_mov_b32_e32 v71, v131
	v_mov_b32_e32 v70, v131
	v_mov_b32_e32 v69, v131
	v_mov_b32_e32 v68, v131
	v_mov_b32_e32 v67, v131
	v_mov_b32_e32 v66, v131
	v_mov_b32_e32 v65, v131
	v_mov_b32_e32 v64, v131
	v_mov_b32_e32 v63, v131
	v_mov_b32_e32 v62, v131
	v_mov_b32_e32 v61, v131
	v_mov_b32_e32 v60, v131
	v_mov_b32_e32 v59, v131
	v_mov_b32_e32 v58, v131
	v_mov_b32_e32 v57, v131
	v_mov_b32_e32 v56, v131
	v_mov_b32_e32 v47, v131
	v_mov_b32_e32 v46, v131
	v_mov_b32_e32 v45, v131
	v_mov_b32_e32 v44, v131
	v_mov_b32_e32 v43, v131
	v_mov_b32_e32 v42, v131
	v_mov_b32_e32 v41, v131
	v_mov_b32_e32 v40, v131
	v_mov_b32_e32 v31, v131
	v_mov_b32_e32 v30, v131
	v_mov_b32_e32 v29, v131
	v_mov_b32_e32 v28, v131
	v_mov_b32_e32 v27, v131
	v_mov_b32_e32 v26, v131
	v_mov_b32_e32 v25, v131
	v_mov_b32_e32 v24, v131
	v_mov_b32_e32 v15, v131
	v_mov_b32_e32 v14, v131
	v_mov_b32_e32 v13, v131
	v_mov_b32_e32 v12, v131
	v_mov_b32_e32 v11, v131
	v_mov_b32_e32 v10, v131
	v_mov_b32_e32 v9, v131
	v_mov_b32_e32 v8, v131
	v_mov_b32_e32 v55, v131
	v_mov_b32_e32 v54, v131
	v_mov_b32_e32 v53, v131
	v_mov_b32_e32 v52, v131
	v_mov_b32_e32 v51, v131
	v_mov_b32_e32 v50, v131
	v_mov_b32_e32 v49, v131
	v_mov_b32_e32 v48, v131
	v_mov_b32_e32 v39, v131
	v_mov_b32_e32 v38, v131
	v_mov_b32_e32 v37, v131
	v_mov_b32_e32 v36, v131
	v_mov_b32_e32 v35, v131
	v_mov_b32_e32 v34, v131
	v_mov_b32_e32 v33, v131
	v_mov_b32_e32 v32, v131
	v_mov_b32_e32 v23, v131
	v_mov_b32_e32 v22, v131
	v_mov_b32_e32 v21, v131
	v_mov_b32_e32 v20, v131
	v_mov_b32_e32 v19, v131
	v_mov_b32_e32 v18, v131
	v_mov_b32_e32 v17, v131
	v_mov_b32_e32 v16, v131
	v_mov_b32_e32 v7, v131
	v_mov_b32_e32 v6, v131
	v_mov_b32_e32 v5, v131
	v_mov_b32_e32 v4, v131
	v_mov_b32_e32 v3, v131
	v_mov_b32_e32 v2, v131
	v_mov_b32_e32 v1, v131
	v_mov_b32_e32 v0, v131
	s_branch .LBB0_986
.Lnz_part:
	s_add_u32 s11, s42, 0x100
	s_addc_u32 s13, s43, 0
	s_add_u32 s42, s44, 0x80
	s_addc_u32 s43, s45, 0
	s_mov_b32 s15, 0
	s_add_i32 s66, s15, 2
	s_add_u32 s20, s42, 0x80
	s_addc_u32 s21, s43, 0
	s_add_i32 s23, 0, 0x10000
	s_cmp_eq_u32 s55, s15
	s_cselect_b32 s45, s19, s21
	s_cselect_b32 s44, s18, s20
	s_cselect_b32 s21, s41, s13
	s_cselect_b32 s20, s40, s11
	s_add_i32 s15, 0, 0x14000
	v_add_u32_e32 v158, s23, v136
	v_add_u32_e32 v174, s15, v136
	ds_read_b128 v[146:149], v158
	ds_read_b128 v[150:153], v158 offset:1024
	ds_read_b128 v[154:157], v158 offset:2048
	ds_read_b128 v[158:161], v158 offset:3072
	ds_read_b128 v[162:165], v174
	ds_read_b128 v[166:169], v174 offset:1024
	ds_read_b128 v[170:173], v174 offset:2048
	ds_read_b128 v[174:177], v174 offset:3072
	v_lshl_add_u64 v[178:179], s[42:43], 0, v[134:135]
	s_add_i32 m0, s17, 0xc000
	ds_read_b128 v[190:193], v145
	ds_read_b128 v[194:197], v145 offset:1024
	ds_read_b128 v[198:201], v145 offset:2048
	ds_read_b128 v[202:205], v145 offset:3072
	ds_read_b128 v[206:209], v145 offset:4096
	ds_read_b128 v[210:213], v145 offset:5120
	ds_read_b128 v[214:217], v145 offset:6144
	ds_read_b128 v[218:221], v145 offset:7168
	global_load_lds_dwordx4 v[178:179], off
	v_lshl_add_u64 v[178:179], s[42:43], 0, v[132:133]
	s_add_i32 m0, s17, 0xe000
	s_nop 0
	global_load_lds_dwordx4 v[178:179], off
	s_waitcnt vmcnt(8)
	s_waitcnt lgkmcnt(0)
	s_barrier
	s_setprio 1
	s_waitcnt lgkmcnt(0)
	v_mfma_f32_16x16x32_bf16 v[128:131], v[146:149], v[190:193], 0
	v_mfma_f32_16x16x32_bf16 v[124:127], v[154:157], v[190:193], 0
	v_mfma_f32_16x16x32_bf16 v[112:115], v[146:149], v[198:201], 0
	v_mfma_f32_16x16x32_bf16 v[108:111], v[154:157], v[198:201], 0
	v_mfma_f32_16x16x32_bf16 v[92:95], v[146:149], v[206:209], 0
	v_mfma_f32_16x16x32_bf16 v[88:91], v[154:157], v[206:209], 0
	v_mfma_f32_16x16x32_bf16 v[76:79], v[146:149], v[214:217], 0
	v_mfma_f32_16x16x32_bf16 v[72:75], v[154:157], v[214:217], 0
	v_mfma_f32_16x16x32_bf16 v[128:131], v[150:153], v[194:197], v[128:131]
	v_mfma_f32_16x16x32_bf16 v[124:127], v[158:161], v[194:197], v[124:127]
	v_mfma_f32_16x16x32_bf16 v[112:115], v[150:153], v[202:205], v[112:115]
	v_mfma_f32_16x16x32_bf16 v[108:111], v[158:161], v[202:205], v[108:111]
	v_mfma_f32_16x16x32_bf16 v[92:95], v[150:153], v[210:213], v[92:95]
	v_mfma_f32_16x16x32_bf16 v[88:91], v[158:161], v[210:213], v[88:91]
	v_mfma_f32_16x16x32_bf16 v[76:79], v[150:153], v[218:221], v[76:79]
	v_mfma_f32_16x16x32_bf16 v[72:75], v[158:161], v[218:221], v[72:75]
	s_setprio 0
	s_setprio 1
	v_mfma_f32_16x16x32_bf16 v[120:123], v[162:165], v[190:193], 0
	v_mfma_f32_16x16x32_bf16 v[116:119], v[170:173], v[190:193], 0
	v_mfma_f32_16x16x32_bf16 v[104:107], v[162:165], v[198:201], 0
	v_mfma_f32_16x16x32_bf16 v[100:103], v[170:173], v[198:201], 0
	v_mfma_f32_16x16x32_bf16 v[84:87], v[162:165], v[206:209], 0
	v_mfma_f32_16x16x32_bf16 v[80:83], v[170:173], v[206:209], 0
	v_mfma_f32_16x16x32_bf16 v[68:71], v[162:165], v[214:217], 0
	v_mfma_f32_16x16x32_bf16 v[64:67], v[170:173], v[214:217], 0
	v_mfma_f32_16x16x32_bf16 v[120:123], v[166:169], v[194:197], v[120:123]
	v_mfma_f32_16x16x32_bf16 v[116:119], v[174:177], v[194:197], v[116:119]
	v_mfma_f32_16x16x32_bf16 v[104:107], v[166:169], v[202:205], v[104:107]
	v_mfma_f32_16x16x32_bf16 v[100:103], v[174:177], v[202:205], v[100:103]
	v_mfma_f32_16x16x32_bf16 v[84:87], v[166:169], v[210:213], v[84:87]
	v_mfma_f32_16x16x32_bf16 v[80:83], v[174:177], v[210:213], v[80:83]
	v_mfma_f32_16x16x32_bf16 v[68:71], v[166:169], v[218:221], v[68:71]
	v_mfma_f32_16x16x32_bf16 v[64:67], v[174:177], v[218:221], v[64:67]
	s_setprio 0
	s_barrier
	s_add_i32 s23, s23, s26
	v_lshl_add_u64 v[178:179], s[20:21], 0, v[96:97]
	s_mov_b32 m0, s23
	ds_read_b128 v[190:193], v145 offset:16384
	ds_read_b128 v[194:197], v145 offset:17408
	ds_read_b128 v[198:201], v145 offset:18432
	ds_read_b128 v[202:205], v145 offset:19456
	ds_read_b128 v[206:209], v145 offset:20480
	ds_read_b128 v[210:213], v145 offset:21504
	ds_read_b128 v[214:217], v145 offset:22528
	ds_read_b128 v[218:221], v145 offset:23552
	global_load_lds_dwordx4 v[178:179], off
	s_add_i32 m0, s23, 0x2000
	v_lshl_add_u64 v[228:229], s[20:21], 0, v[188:189]
	s_add_u32 s20, s20, s68
	s_addc_u32 s21, s21, 0
	s_add_i32 s15, s15, s26
	global_load_lds_dwordx4 v[228:229], off
	v_lshl_add_u64 v[234:235], s[20:21], 0, v[96:97]
	s_mov_b32 m0, s15
	v_lshl_add_u64 v[236:237], s[20:21], 0, v[188:189]
	global_load_lds_dwordx4 v[234:235], off
	s_add_i32 m0, s15, 0x2000
	v_lshl_add_u64 v[238:239], s[44:45], 0, v[96:97]
	global_load_lds_dwordx4 v[236:237], off
	s_mov_b32 m0, s17
	v_lshl_add_u64 v[240:241], s[44:45], 0, v[188:189]
	global_load_lds_dwordx4 v[238:239], off
	s_mov_b32 m0, s47
	s_nop 0
	global_load_lds_dwordx4 v[240:241], off
	s_waitcnt vmcnt(8)
	s_waitcnt lgkmcnt(0)
	s_barrier
	s_setprio 1
	s_waitcnt lgkmcnt(0)
	v_mfma_f32_16x16x32_bf16 v[60:63], v[146:149], v[190:193], 0
	v_mfma_f32_16x16x32_bf16 v[56:59], v[154:157], v[190:193], 0
	v_mfma_f32_16x16x32_bf16 v[44:47], v[146:149], v[198:201], 0
	v_mfma_f32_16x16x32_bf16 v[40:43], v[154:157], v[198:201], 0
	v_mfma_f32_16x16x32_bf16 v[28:31], v[146:149], v[206:209], 0
	v_mfma_f32_16x16x32_bf16 v[24:27], v[154:157], v[206:209], 0
	v_mfma_f32_16x16x32_bf16 v[12:15], v[146:149], v[214:217], 0
	v_mfma_f32_16x16x32_bf16 v[8:11], v[154:157], v[214:217], 0
	v_mfma_f32_16x16x32_bf16 v[60:63], v[150:153], v[194:197], v[60:63]
	v_mfma_f32_16x16x32_bf16 v[56:59], v[158:161], v[194:197], v[56:59]
	v_mfma_f32_16x16x32_bf16 v[44:47], v[150:153], v[202:205], v[44:47]
	v_mfma_f32_16x16x32_bf16 v[40:43], v[158:161], v[202:205], v[40:43]
	v_mfma_f32_16x16x32_bf16 v[28:31], v[150:153], v[210:213], v[28:31]
	v_mfma_f32_16x16x32_bf16 v[24:27], v[158:161], v[210:213], v[24:27]
	v_mfma_f32_16x16x32_bf16 v[12:15], v[150:153], v[218:221], v[12:15]
	v_mfma_f32_16x16x32_bf16 v[8:11], v[158:161], v[218:221], v[8:11]
	s_setprio 0
	s_setprio 1
	v_mfma_f32_16x16x32_bf16 v[52:55], v[162:165], v[190:193], 0
	v_mfma_f32_16x16x32_bf16 v[48:51], v[170:173], v[190:193], 0
	v_mfma_f32_16x16x32_bf16 v[36:39], v[162:165], v[198:201], 0
	v_mfma_f32_16x16x32_bf16 v[32:35], v[170:173], v[198:201], 0
	v_mfma_f32_16x16x32_bf16 v[20:23], v[162:165], v[206:209], 0
	v_mfma_f32_16x16x32_bf16 v[16:19], v[170:173], v[206:209], 0
	v_mfma_f32_16x16x32_bf16 v[4:7], v[162:165], v[214:217], 0
	v_mfma_f32_16x16x32_bf16 v[0:3], v[170:173], v[214:217], 0
	v_mfma_f32_16x16x32_bf16 v[52:55], v[166:169], v[194:197], v[52:55]
	v_mfma_f32_16x16x32_bf16 v[48:51], v[174:177], v[194:197], v[48:51]
	v_mfma_f32_16x16x32_bf16 v[36:39], v[166:169], v[202:205], v[36:39]
	v_mfma_f32_16x16x32_bf16 v[32:35], v[174:177], v[202:205], v[32:35]
	v_mfma_f32_16x16x32_bf16 v[20:23], v[166:169], v[210:213], v[20:23]
	v_mfma_f32_16x16x32_bf16 v[16:19], v[174:177], v[210:213], v[16:19]
	v_mfma_f32_16x16x32_bf16 v[4:7], v[166:169], v[218:221], v[4:7]
	v_mfma_f32_16x16x32_bf16 v[0:3], v[174:177], v[218:221], v[0:3]
	s_setprio 0
	s_barrier
	s_add_i32 s15, 0, 0x18000
	s_add_i32 s23, 0, 0x1c000
	v_add_u32_e32 v158, s15, v136
	v_add_u32_e32 v174, s23, v136
	ds_read_b128 v[146:149], v158
	ds_read_b128 v[150:153], v158 offset:1024
	ds_read_b128 v[154:157], v158 offset:2048
	ds_read_b128 v[158:161], v158 offset:3072
	ds_read_b128 v[162:165], v174
	ds_read_b128 v[166:169], v174 offset:1024
	ds_read_b128 v[170:173], v174 offset:2048
	ds_read_b128 v[174:177], v174 offset:3072
	s_add_u32 s20, s44, s68
	s_addc_u32 s21, s45, 0
	s_mov_b32 m0, s48
	v_lshl_add_u64 v[242:243], s[20:21], 0, v[96:97]
	ds_read_b128 v[190:193], v145 offset:32768
	ds_read_b128 v[194:197], v145 offset:33792
	ds_read_b128 v[198:201], v145 offset:34816
	ds_read_b128 v[202:205], v145 offset:35840
	ds_read_b128 v[206:209], v145 offset:36864
	ds_read_b128 v[210:213], v145 offset:37888
	ds_read_b128 v[214:217], v145 offset:38912
	ds_read_b128 v[218:221], v145 offset:39936
	global_load_lds_dwordx4 v[242:243], off
	v_lshl_add_u64 v[242:243], s[20:21], 0, v[188:189]
	s_mov_b32 m0, s49
	s_nop 0
	global_load_lds_dwordx4 v[242:243], off
	s_waitcnt vmcnt(8)
	s_waitcnt lgkmcnt(0)
	s_barrier
	s_setprio 1
	s_waitcnt lgkmcnt(0)
	v_mfma_f32_16x16x32_bf16 v[128:131], v[146:149], v[190:193], v[128:131]
	v_mfma_f32_16x16x32_bf16 v[124:127], v[154:157], v[190:193], v[124:127]
	v_mfma_f32_16x16x32_bf16 v[112:115], v[146:149], v[198:201], v[112:115]
	v_mfma_f32_16x16x32_bf16 v[108:111], v[154:157], v[198:201], v[108:111]
	v_mfma_f32_16x16x32_bf16 v[92:95], v[146:149], v[206:209], v[92:95]
	v_mfma_f32_16x16x32_bf16 v[88:91], v[154:157], v[206:209], v[88:91]
	v_mfma_f32_16x16x32_bf16 v[76:79], v[146:149], v[214:217], v[76:79]
	v_mfma_f32_16x16x32_bf16 v[72:75], v[154:157], v[214:217], v[72:75]
	v_mfma_f32_16x16x32_bf16 v[128:131], v[150:153], v[194:197], v[128:131]
	v_mfma_f32_16x16x32_bf16 v[124:127], v[158:161], v[194:197], v[124:127]
	v_mfma_f32_16x16x32_bf16 v[112:115], v[150:153], v[202:205], v[112:115]
	v_mfma_f32_16x16x32_bf16 v[108:111], v[158:161], v[202:205], v[108:111]
	v_mfma_f32_16x16x32_bf16 v[92:95], v[150:153], v[210:213], v[92:95]
	v_mfma_f32_16x16x32_bf16 v[88:91], v[158:161], v[210:213], v[88:91]
	v_mfma_f32_16x16x32_bf16 v[76:79], v[150:153], v[218:221], v[76:79]
	v_mfma_f32_16x16x32_bf16 v[72:75], v[158:161], v[218:221], v[72:75]
	s_setprio 0
	s_setprio 1
	v_mfma_f32_16x16x32_bf16 v[120:123], v[162:165], v[190:193], v[120:123]
	v_mfma_f32_16x16x32_bf16 v[116:119], v[170:173], v[190:193], v[116:119]
	v_mfma_f32_16x16x32_bf16 v[104:107], v[162:165], v[198:201], v[104:107]
	v_mfma_f32_16x16x32_bf16 v[100:103], v[170:173], v[198:201], v[100:103]
	v_mfma_f32_16x16x32_bf16 v[84:87], v[162:165], v[206:209], v[84:87]
	v_mfma_f32_16x16x32_bf16 v[80:83], v[170:173], v[206:209], v[80:83]
	v_mfma_f32_16x16x32_bf16 v[68:71], v[162:165], v[214:217], v[68:71]
	v_mfma_f32_16x16x32_bf16 v[64:67], v[170:173], v[214:217], v[64:67]
	v_mfma_f32_16x16x32_bf16 v[120:123], v[166:169], v[194:197], v[120:123]
	v_mfma_f32_16x16x32_bf16 v[116:119], v[174:177], v[194:197], v[116:119]
	v_mfma_f32_16x16x32_bf16 v[104:107], v[166:169], v[202:205], v[104:107]
	v_mfma_f32_16x16x32_bf16 v[100:103], v[174:177], v[202:205], v[100:103]
	v_mfma_f32_16x16x32_bf16 v[84:87], v[166:169], v[210:213], v[84:87]
	v_mfma_f32_16x16x32_bf16 v[80:83], v[174:177], v[210:213], v[80:83]
	v_mfma_f32_16x16x32_bf16 v[68:71], v[166:169], v[218:221], v[68:71]
	v_mfma_f32_16x16x32_bf16 v[64:67], v[174:177], v[218:221], v[64:67]
	s_setprio 0
	s_barrier
	s_add_i32 s15, s15, s26
	v_lshl_add_u64 v[178:179], v[178:179], 0, s[30:31]
	s_mov_b32 m0, s15
	ds_read_b128 v[190:193], v145 offset:49152
	ds_read_b128 v[194:197], v145 offset:50176
	ds_read_b128 v[198:201], v145 offset:51200
	ds_read_b128 v[202:205], v145 offset:52224
	ds_read_b128 v[206:209], v145 offset:53248
	ds_read_b128 v[210:213], v145 offset:54272
	ds_read_b128 v[214:217], v145 offset:55296
	ds_read_b128 v[218:221], v145 offset:56320
	global_load_lds_dwordx4 v[178:179], off
	v_lshl_add_u64 v[178:179], v[228:229], 0, s[30:31]
	s_add_i32 m0, s15, 0x2000
	s_add_i32 s15, s23, s26
	global_load_lds_dwordx4 v[178:179], off
	v_lshl_add_u64 v[178:179], v[234:235], 0, s[30:31]
	s_mov_b32 m0, s15
	s_nop 0
	global_load_lds_dwordx4 v[178:179], off
	v_lshl_add_u64 v[178:179], v[236:237], 0, s[30:31]
	s_add_i32 m0, s15, 0x2000
	s_nop 0
	global_load_lds_dwordx4 v[178:179], off
	v_lshl_add_u64 v[178:179], v[238:239], 0, s[30:31]
	s_mov_b32 m0, s53
	s_nop 0
	global_load_lds_dwordx4 v[178:179], off
	v_lshl_add_u64 v[178:179], v[240:241], 0, s[30:31]
	s_mov_b32 m0, s54
	s_nop 0
	global_load_lds_dwordx4 v[178:179], off
	s_waitcnt vmcnt(8)
	s_waitcnt lgkmcnt(0)
	s_barrier
	s_setprio 1
	s_waitcnt lgkmcnt(0)
	v_mfma_f32_16x16x32_bf16 v[60:63], v[146:149], v[190:193], v[60:63]
	v_mfma_f32_16x16x32_bf16 v[56:59], v[154:157], v[190:193], v[56:59]
	v_mfma_f32_16x16x32_bf16 v[44:47], v[146:149], v[198:201], v[44:47]
	v_mfma_f32_16x16x32_bf16 v[40:43], v[154:157], v[198:201], v[40:43]
	v_mfma_f32_16x16x32_bf16 v[28:31], v[146:149], v[206:209], v[28:31]
	v_mfma_f32_16x16x32_bf16 v[24:27], v[154:157], v[206:209], v[24:27]
	v_mfma_f32_16x16x32_bf16 v[12:15], v[146:149], v[214:217], v[12:15]
	v_mfma_f32_16x16x32_bf16 v[8:11], v[154:157], v[214:217], v[8:11]
	v_mfma_f32_16x16x32_bf16 v[60:63], v[150:153], v[194:197], v[60:63]
	v_mfma_f32_16x16x32_bf16 v[56:59], v[158:161], v[194:197], v[56:59]
	v_mfma_f32_16x16x32_bf16 v[44:47], v[150:153], v[202:205], v[44:47]
	v_mfma_f32_16x16x32_bf16 v[40:43], v[158:161], v[202:205], v[40:43]
	v_mfma_f32_16x16x32_bf16 v[28:31], v[150:153], v[210:213], v[28:31]
	v_mfma_f32_16x16x32_bf16 v[24:27], v[158:161], v[210:213], v[24:27]
	v_mfma_f32_16x16x32_bf16 v[12:15], v[150:153], v[218:221], v[12:15]
	v_mfma_f32_16x16x32_bf16 v[8:11], v[158:161], v[218:221], v[8:11]
	s_setprio 0
	s_setprio 1
	v_mfma_f32_16x16x32_bf16 v[52:55], v[162:165], v[190:193], v[52:55]
	v_mfma_f32_16x16x32_bf16 v[48:51], v[170:173], v[190:193], v[48:51]
	v_mfma_f32_16x16x32_bf16 v[36:39], v[162:165], v[198:201], v[36:39]
	v_mfma_f32_16x16x32_bf16 v[32:35], v[170:173], v[198:201], v[32:35]
	v_mfma_f32_16x16x32_bf16 v[20:23], v[162:165], v[206:209], v[20:23]
	v_mfma_f32_16x16x32_bf16 v[16:19], v[170:173], v[206:209], v[16:19]
	v_mfma_f32_16x16x32_bf16 v[4:7], v[162:165], v[214:217], v[4:7]
	v_mfma_f32_16x16x32_bf16 v[0:3], v[170:173], v[214:217], v[0:3]
	v_mfma_f32_16x16x32_bf16 v[52:55], v[166:169], v[194:197], v[52:55]
	v_mfma_f32_16x16x32_bf16 v[48:51], v[174:177], v[194:197], v[48:51]
	v_mfma_f32_16x16x32_bf16 v[36:39], v[166:169], v[202:205], v[36:39]
	v_mfma_f32_16x16x32_bf16 v[32:35], v[174:177], v[202:205], v[32:35]
	v_mfma_f32_16x16x32_bf16 v[20:23], v[166:169], v[210:213], v[20:23]
	v_mfma_f32_16x16x32_bf16 v[16:19], v[174:177], v[210:213], v[16:19]
	v_mfma_f32_16x16x32_bf16 v[4:7], v[166:169], v[218:221], v[4:7]
	v_mfma_f32_16x16x32_bf16 v[0:3], v[174:177], v[218:221], v[0:3]
	s_setprio 0
	s_barrier
	s_add_u32 s11, s11, 0x100
	s_addc_u32 s13, s13, 0
	s_add_u32 s42, s42, 0x100
	s_addc_u32 s43, s43, 0
	s_cmp_ge_i32 s66, s50
	s_mov_b32 s15, s66
	s_cbranch_scc1 .Lpeel_exit_part

.Lpeel_exit_part:
.LBB0_986:
	s_and_b64 vcc, exec, s[8:9]
	s_cbranch_vccz .LBB0_988
	s_barrier
